# phase 4: hand-written EpiLora epilogue (saddr stores, same op sequence, no 64-bit address math)
# speedup vs baseline: 1.0891x; 1.0015x over previous
; #define GLOAD(kt) do { const int ko = (kt) * BK; \
;     ra0 = *(const uint4*)(gA + ko); ra1 = *(const uint4*)(gA + sA + ko); ra2 = *(const uint4*)(gA + 2 * sA + ko); ra3 = *(const uint4*)(gA + 3 * sA + ko); \
;     rb0 = *(const uint4*)(gB + ko); rb1 = *(const uint4*)(gB + sB + ko); rb2 = *(const uint4*)(gB + 2 * sB + ko); rb3 = *(const uint4*)(gB + 3 * sB + ko); } while (0)
; #define LSTORE(st) do { \
;     *(uint4*)(lA + (st) * ASZ) = ra0; *(uint4*)(lA + (st) * ASZ + 64 * LDT) = ra1; *(uint4*)(lA + (st) * ASZ + 128 * LDT) = ra2; *(uint4*)(lA + (st) * ASZ + 192 * LDT) = ra3; \
;     *(uint4*)(lB + (st) * BSZ) = rb0; *(uint4*)(lB + (st) * BSZ + 64 * LDT) = rb1; *(uint4*)(lB + (st) * BSZ + 128 * LDT) = rb2; *(uint4*)(lB + (st) * BSZ + 192 * LDT) = rb3; } while (0)
; template <class Epi>
; DI void gemm_tile(const GemmDesc g, int m0, int n0, unsigned char* lds, Epi& epi) {
;     ...
;   const int nk = g.K / BK;
;   const bf16_t* gA = g.A + (size_t)(m0 + (tid >> 3)) * g.lda + (tid & 7) * 8;
;   const bf16_t* gB = g.Bt + (size_t)(n0 + (tid >> 3)) * g.ldb + (tid & 7) * 8;
;   const size_t sA = (size_t)64 * g.lda, sB = (size_t)64 * g.ldb;
;   bf16_t* lA = As + (tid >> 3) * LDT + (tid & 7) * 8;
;   bf16_t* lB = Bs + (tid >> 3) * LDT + (tid & 7) * 8;
;   const bf16_t* fA = As + (wm * 128 + (lane & 31)) * LDT + (lane >> 5) * 8;
;   const bf16_t* fB = Bs + (wn * 64 + (lane & 31)) * LDT + (lane >> 5) * 8;
;     ...
;   __syncthreads();
;   GLOAD(0);
;   LSTORE(0);
;   __syncthreads();
;   for (int kt = 0; kt < nk; kt += 2) {
;     const bool h1 = kt + 1 < nk, h2 = kt + 2 < nk;
;     if (h1) GLOAD(kt + 1);
;     COMPUTE(0);
;     if (h1) LSTORE(1);
;     __syncthreads();
; DI void phase4(const Params& P, unsigned char* lds) {
;     ...
;     if (r < nl) { const int g = r / 132, rr = r % 132, tm = rr >> 1, tn = rr & 1; const int d = g & 1, isA = g >> 1;
;       GemmDesc gd{(const bf16_t*)(P.ws + OFF_LW) + g * 64, 256, (const bf16_t*)(P.ws + OFF_WL_T) + (size_t)g * 512 * 64, 64, 64};
;       EpiLora e{(bf16_t*)(P.ws + (isA ? OFF_A : OFF_E) + d * SZ_ARR), (isA ? P.rw_a0 : P.rw_w0) + d * 512, isA};
;       gemm_tile(gd, tm * BM, tn * BN, lds, e); continue; }
.LBB0_1045:
	s_mul_hi_i32 s0, s2, 0x3e0f83e1
	s_lshr_b32 s1, s0, 31
	s_ashr_i32 s0, s0, 5
	s_add_i32 s4, s0, s1
	s_lshl_b32 s6, s4, 6
	s_mul_i32 s0, s4, 0x84
	s_ashr_i32 s7, s6, 31
	s_sub_i32 s0, s2, s0
	s_and_b32 s1, s4, 1
	s_lshl_b64 s[6:7], s[6:7], 1
	s_add_u32 s8, s3, s6
	s_addc_u32 s9, s54, s7
	s_ashr_i32 s5, s4, 31
	s_lshl_b64 s[6:7], s[4:5], 16
	s_add_u32 s10, s55, s6
	s_addc_u32 s11, s56, s7
	s_cmp_lt_u32 s4, 2
	s_cselect_b64 vcc, -1, 0
	s_and_b64 s[4:5], vcc, exec
	s_mov_b32 s4, 0xb00000
	v_readlane_b32 s12, v243, 2
	s_cselect_b32 s4, s4, 0x2c00000
	v_readlane_b32 s14, v243, 4
	v_readlane_b32 s15, v243, 5
	v_readlane_b32 s18, v243, 8
	v_readlane_b32 s19, v243, 9
	s_cselect_b32 s7, s15, s19
	s_cselect_b32 s6, s14, s18
	s_add_u32 s4, s94, s4
	s_mul_i32 s5, s1, 0x1080000
	s_addc_u32 s12, s95, 0
	s_add_u32 s4, s4, s5
	s_addc_u32 s5, s12, 0
	s_lshl_b32 s1, s1, 11
	s_add_u32 s6, s6, s1
	s_addc_u32 s7, s7, 0
	s_lshl_b32 s1, s0, 7
	v_mov_b32_e32 v202, v208
	s_and_b32 s1, s1, 0xffffff00
	s_lshl_b32 s0, s0, 8
	v_ashrrev_i32_e32 v33, 3, v202
	v_add_u32_e32 v0, s1, v33
	v_ashrrev_i32_e32 v1, 31, v0
	v_lshlrev_b64 v[0:1], 9, v[0:1]
	v_lshlrev_b32_e32 v2, 4, v202
	s_and_b32 s0, s0, 0x100
	v_lshl_add_u64 v[0:1], s[8:9], 0, v[0:1]
	v_and_b32_e32 v148, 0x70, v2
	v_lshl_add_u64 v[8:9], v[0:1], 0, v[148:149]
	v_add_u32_e32 v0, s0, v33
	v_ashrrev_i32_e32 v1, 31, v0
	v_lshlrev_b64 v[0:1], 7, v[0:1]
	v_lshl_add_u64 v[0:1], s[10:11], 0, v[0:1]
	v_cndmask_b32_e32 v201, 1.0, v200, vcc
	v_lshl_add_u64 v[24:25], v[0:1], 0, v[148:149]
	v_add_co_u32_e32 v0, vcc, s64, v8
	s_movk_i32 s8, 0x2000
	s_nop 0
	v_addc_co_u32_e32 v1, vcc, 0, v9, vcc
	v_add_co_u32_e32 v4, vcc, s65, v8
	s_waitcnt vmcnt(63) expcnt(7) lgkmcnt(15)
	s_nop 0
	v_addc_co_u32_e32 v5, vcc, 0, v9, vcc
	v_add_co_u32_e32 v16, vcc, s66, v8
	s_barrier
	s_nop 0
	v_addc_co_u32_e32 v17, vcc, 0, v9, vcc
	v_add_co_u32_e32 v20, vcc, s8, v24
	s_movk_i32 s8, 0x6000
	s_nop 0
	v_addc_co_u32_e32 v21, vcc, 0, v25, vcc
	v_add_co_u32_e32 v26, vcc, s67, v24
	s_nop 1
	v_addc_co_u32_e32 v27, vcc, 0, v25, vcc
	v_add_co_u32_e32 v28, vcc, s8, v24
	global_load_dwordx4 v[0:3], v[0:1], off
	s_nop 0
	global_load_dwordx4 v[4:7], v[4:5], off
	v_addc_co_u32_e32 v29, vcc, 0, v25, vcc
	global_load_dwordx4 v[8:11], v[8:9], off
	s_nop 0
	global_load_dwordx4 v[12:15], v[24:25], off
	s_nop 0
	global_load_dwordx4 v[16:19], v[16:17], off
	s_nop 0
	global_load_dwordx4 v[20:23], v[20:21], off
	s_nop 0
	global_load_dwordx4 v[24:27], v[26:27], off
	s_nop 0
	global_load_dwordx4 v[28:31], v[28:29], off
	v_ashrrev_i32_e32 v32, 1, v202
	v_and_b32_e32 v203, 31, v202
	v_bfe_u32 v218, v202, 5, 1
	v_and_b32_e32 v219, 0xffffff80, v32
	v_lshlrev_b32_e32 v32, 4, v218
	v_mad_u64_u32 v[34:35], s[8:9], v33, s62, v[148:149]
	v_or_b32_e32 v33, v219, v203
	v_mad_u64_u32 v[164:165], s[8:9], v33, s62, v[32:33]
	v_add_u32_e32 v35, 0x12000, v34
	v_readlane_b32 s13, v243, 3
	v_readlane_b32 s16, v243, 6
	v_readlane_b32 s17, v243, 7
	v_readlane_b32 s20, v243, 10
	v_readlane_b32 s21, v243, 11
	v_readlane_b32 s22, v243, 12
	v_readlane_b32 s23, v243, 13
	v_readlane_b32 s24, v243, 14
	v_readlane_b32 s25, v243, 15
	v_readlane_b32 s26, v243, 16
	v_readlane_b32 s27, v243, 17
	s_waitcnt vmcnt(5)
	ds_write_b128 v34, v[8:11]
	s_waitcnt vmcnt(4)
	ds_write_b128 v35, v[12:15]
	ds_write_b128 v34, v[0:3] offset:9216
	ds_write_b128 v34, v[4:7] offset:18432
	s_waitcnt vmcnt(3)
	ds_write_b128 v34, v[16:19] offset:27648
	s_waitcnt vmcnt(2)
	ds_write_b128 v35, v[20:23] offset:9216
	s_waitcnt vmcnt(1)
	ds_write_b128 v35, v[24:27] offset:18432
	s_waitcnt vmcnt(0)
	ds_write_b128 v35, v[28:31] offset:27648
	s_waitcnt lgkmcnt(0)
	s_barrier
	ds_read_b128 v[0:3], v164
	v_and_b32_e32 v4, 0xdf, v202
	v_mul_u32_u24_e32 v4, 0x90, v4
	v_add3_u32 v148, v4, v32, s63
	ds_read_b128 v[4:7], v148
	ds_read_b128 v[128:131], v164 offset:32
	ds_read_b128 v[132:135], v148 offset:32
	ds_read_b128 v[8:11], v148 offset:4608
	ds_read_b128 v[136:139], v148 offset:4640
	s_waitcnt lgkmcnt(4)
	v_mfma_f32_32x32x16_bf16 v[112:127], v[0:3], v[4:7], 0
	s_waitcnt lgkmcnt(1)
	v_mfma_f32_32x32x16_bf16 v[96:111], v[0:3], v[8:11], 0
	ds_read_b128 v[0:3], v164 offset:4608
	ds_read_b128 v[140:143], v164 offset:4640
	s_waitcnt lgkmcnt(1)
	v_mfma_f32_32x32x16_bf16 v[80:95], v[0:3], v[4:7], 0
	v_mfma_f32_32x32x16_bf16 v[64:79], v[0:3], v[8:11], 0
	ds_read_b128 v[0:3], v164 offset:9216
	ds_read_b128 v[144:147], v164 offset:9248
	s_waitcnt lgkmcnt(1)
	v_mfma_f32_32x32x16_bf16 v[48:63], v[0:3], v[4:7], 0
	v_mfma_f32_32x32x16_bf16 v[32:47], v[0:3], v[8:11], 0
	ds_read_b128 v[0:3], v164 offset:13824
	ds_read_b128 v[150:153], v164 offset:13856
	s_waitcnt lgkmcnt(1)
	v_mfma_f32_32x32x16_bf16 v[16:31], v[0:3], v[4:7], 0
	v_mfma_f32_32x32x16_bf16 v[0:15], v[0:3], v[8:11], 0
	v_mfma_f32_32x32x16_bf16 v[112:127], v[128:131], v[132:135], v[112:127]
	v_mfma_f32_32x32x16_bf16 v[96:111], v[128:131], v[136:139], v[96:111]
	v_mfma_f32_32x32x16_bf16 v[80:95], v[140:143], v[132:135], v[80:95]
	v_mfma_f32_32x32x16_bf16 v[64:79], v[140:143], v[136:139], v[64:79]
	v_mfma_f32_32x32x16_bf16 v[48:63], v[144:147], v[132:135], v[48:63]
	v_mfma_f32_32x32x16_bf16 v[32:47], v[144:147], v[136:139], v[32:47]
	s_waitcnt lgkmcnt(0)
	v_mfma_f32_32x32x16_bf16 v[16:31], v[150:153], v[132:135], v[16:31]
	v_mfma_f32_32x32x16_bf16 v[0:15], v[150:153], v[136:139], v[0:15]
	ds_read_b128 v[136:139], v164 offset:64
	ds_read_b128 v[152:155], v148 offset:64
	ds_read_b128 v[204:207], v164 offset:96
	ds_read_b128 v[132:135], v148 offset:96
	ds_read_b128 v[156:159], v148 offset:4672
	ds_read_b128 v[128:131], v148 offset:4704
	v_and_b32_e32 v148, 0xc0, v202
	v_add_u32_e32 v150, s1, v219
	v_or3_b32 v148, v148, s0, v203
	v_lshl_or_b32 v150, v218, 2, v150
	v_lshlrev_b32_e32 v203, 2, v148
	v_ashrrev_i32_e32 v151, 31, v150
	s_waitcnt lgkmcnt(4)
	v_mfma_f32_32x32x16_bf16 v[112:127], v[136:139], v[152:155], v[112:127]
	ds_read_b128 v[160:163], v164 offset:4672
	ds_read_b128 v[144:147], v164 offset:4704
	ds_read_b128 v[210:213], v164 offset:9280
	ds_read_b128 v[140:143], v164 offset:9312
	v_lshlrev_b64 v[218:219], 10, v[150:151]
	v_lshlrev_b32_e32 v148, 1, v148
	s_waitcnt lgkmcnt(5)
	v_mfma_f32_32x32x16_bf16 v[96:111], v[136:139], v[156:159], v[96:111]
	ds_read_b128 v[214:217], v164 offset:13888
	ds_read_b128 v[136:139], v164 offset:13920
	s_waitcnt lgkmcnt(0)
	s_barrier
	v_mfma_f32_32x32x16_bf16 v[112:127], v[204:207], v[132:135], v[112:127]
	v_mfma_f32_32x32x16_bf16 v[96:111], v[204:207], v[128:131], v[96:111]
	v_and_b32_e32 v148, 0xc0, v208
	v_and_b32_e32 v203, 31, v208
	v_or3_b32 v148, v148, s0, v203
	v_lshlrev_b32_e32 v203, 2, v148
	global_load_dword v202, v203, s[6:7]
	global_load_dword v151, v203, s[6:7] offset:128
	v_mfma_f32_32x32x16_bf16 v[80:95], v[160:163], v[152:155], v[80:95]
	v_lshrrev_b32_e32 v150, 8, v208
	v_bfe_u32 v218, v208, 5, 1
	v_lshlrev_b32_e32 v150, 7, v150
	v_lshl_or_b32 v150, v218, 2, v150
	v_add_u32_e32 v150, s1, v150
	v_mfma_f32_32x32x16_bf16 v[64:79], v[160:163], v[156:159], v[64:79]
	v_lshlrev_b32_e32 v150, 10, v150
	v_lshl_add_u32 v150, v148, 1, v150
	v_mfma_f32_32x32x16_bf16 v[80:95], v[144:147], v[132:135], v[80:95]
	v_mfma_f32_32x32x16_bf16 v[64:79], v[144:147], v[128:131], v[64:79]
	s_waitcnt vmcnt(0)
	s_nop 7
	v_add_f32_e32 v112, v112, v202
	v_add_f32_e32 v113, v113, v202
	v_add_f32_e32 v114, v114, v202
	v_add_f32_e32 v115, v115, v202
	v_add_f32_e32 v116, v116, v202
	v_add_f32_e32 v117, v117, v202
	v_mfma_f32_32x32x16_bf16 v[48:63], v[210:213], v[152:155], v[48:63]
	v_add_f32_e32 v118, v118, v202
	v_add_f32_e32 v119, v119, v202
	v_add_f32_e32 v120, v120, v202
	v_add_f32_e32 v121, v121, v202
	v_add_f32_e32 v122, v122, v202
	v_add_f32_e32 v123, v123, v202
	v_mfma_f32_32x32x16_bf16 v[16:31], v[214:217], v[152:155], v[16:31]
	v_add_f32_e32 v124, v124, v202
	v_add_f32_e32 v125, v125, v202
	v_add_f32_e32 v126, v126, v202
	v_add_f32_e32 v127, v127, v202
	v_mul_f32_e32 v112, 0xbfb8aa3b, v112
	v_mul_f32_e32 v113, 0xbfb8aa3b, v113
	v_mfma_f32_32x32x16_bf16 v[48:63], v[140:143], v[132:135], v[48:63]
	v_mul_f32_e32 v114, 0xbfb8aa3b, v114
	v_mul_f32_e32 v115, 0xbfb8aa3b, v115
	v_mul_f32_e32 v116, 0xbfb8aa3b, v116
	v_mul_f32_e32 v117, 0xbfb8aa3b, v117
	v_mul_f32_e32 v118, 0xbfb8aa3b, v118
	v_mul_f32_e32 v119, 0xbfb8aa3b, v119
	v_mfma_f32_32x32x16_bf16 v[16:31], v[136:139], v[132:135], v[16:31]
	v_mul_f32_e32 v120, 0xbfb8aa3b, v120
	v_mul_f32_e32 v121, 0xbfb8aa3b, v121
	v_mul_f32_e32 v122, 0xbfb8aa3b, v122
	v_mul_f32_e32 v123, 0xbfb8aa3b, v123
	v_mul_f32_e32 v124, 0xbfb8aa3b, v124
	v_mul_f32_e32 v125, 0xbfb8aa3b, v125
	v_mfma_f32_32x32x16_bf16 v[32:47], v[210:213], v[156:159], v[32:47]
	v_mul_f32_e32 v126, 0xbfb8aa3b, v126
	v_mul_f32_e32 v127, 0xbfb8aa3b, v127
	v_exp_f32_e32 v112, v112
	v_exp_f32_e32 v113, v113
	v_exp_f32_e32 v114, v114
	v_exp_f32_e32 v115, v115
	v_mfma_f32_32x32x16_bf16 v[0:15], v[214:217], v[156:159], v[0:15]
	v_exp_f32_e32 v116, v116
	v_exp_f32_e32 v117, v117
	v_exp_f32_e32 v118, v118
	v_exp_f32_e32 v119, v119
	v_exp_f32_e32 v120, v120
	v_exp_f32_e32 v121, v121
	v_mfma_f32_32x32x16_bf16 v[32:47], v[140:143], v[128:131], v[32:47]
	v_exp_f32_e32 v122, v122
	v_exp_f32_e32 v123, v123
	v_exp_f32_e32 v124, v124
	v_exp_f32_e32 v125, v125
	v_exp_f32_e32 v126, v126
	v_exp_f32_e32 v127, v127
	v_mfma_f32_32x32x16_bf16 v[0:15], v[136:139], v[128:131], v[0:15]
	v_add_f32_e32 v112, 1.0, v112
	v_add_f32_e32 v113, 1.0, v113
	v_add_f32_e32 v114, 1.0, v114
	v_add_f32_e32 v115, 1.0, v115
	v_add_f32_e32 v116, 1.0, v116
	v_add_f32_e32 v117, 1.0, v117
	v_add_f32_e32 v118, 1.0, v118
	v_add_f32_e32 v119, 1.0, v119
	v_add_f32_e32 v120, 1.0, v120
	v_add_f32_e32 v121, 1.0, v121
	v_add_f32_e32 v122, 1.0, v122
	v_add_f32_e32 v123, 1.0, v123
	v_add_f32_e32 v124, 1.0, v124
	v_add_f32_e32 v125, 1.0, v125
	v_add_f32_e32 v126, 1.0, v126
	v_add_f32_e32 v127, 1.0, v127
	v_rcp_f32_e32 v112, v112
	v_rcp_f32_e32 v113, v113
	v_rcp_f32_e32 v114, v114
	v_rcp_f32_e32 v115, v115
	v_rcp_f32_e32 v116, v116
	v_rcp_f32_e32 v117, v117
	v_rcp_f32_e32 v118, v118
	v_rcp_f32_e32 v119, v119
	v_rcp_f32_e32 v120, v120
	v_rcp_f32_e32 v121, v121
	v_rcp_f32_e32 v122, v122
	v_rcp_f32_e32 v123, v123
	v_rcp_f32_e32 v124, v124
	v_rcp_f32_e32 v125, v125
	v_rcp_f32_e32 v126, v126
	v_rcp_f32_e32 v127, v127
	v_mul_f32_e32 v112, v201, v112
	v_mul_f32_e32 v113, v201, v113
	v_mul_f32_e32 v114, v201, v114
	v_mul_f32_e32 v115, v201, v115
	v_mul_f32_e32 v116, v201, v116
	v_mul_f32_e32 v117, v201, v117
	v_mul_f32_e32 v118, v201, v118
	v_mul_f32_e32 v119, v201, v119
	v_mul_f32_e32 v120, v201, v120
	v_mul_f32_e32 v121, v201, v121
	v_mul_f32_e32 v122, v201, v122
	v_mul_f32_e32 v123, v201, v123
	v_mul_f32_e32 v124, v201, v124
	v_mul_f32_e32 v125, v201, v125
	v_mul_f32_e32 v126, v201, v126
	v_mul_f32_e32 v127, v201, v127
	v_cvt_pk_bf16_f32 v112, v112, v113
	v_cvt_pk_bf16_f32 v113, v114, v115
	v_cvt_pk_bf16_f32 v114, v116, v117
	v_cvt_pk_bf16_f32 v115, v118, v119
	v_cvt_pk_bf16_f32 v116, v120, v121
	v_cvt_pk_bf16_f32 v117, v122, v123
	v_cvt_pk_bf16_f32 v118, v124, v125
	v_cvt_pk_bf16_f32 v119, v126, v127
	global_store_short v150, v112, s[4:5] offset:0
	global_store_short_d16_hi v150, v112, s[4:5] offset:1024
	global_store_short v150, v113, s[4:5] offset:2048
	global_store_short_d16_hi v150, v113, s[4:5] offset:3072
	v_add_u32_e32 v218, 0x2000, v150
	global_store_short v218, v114, s[4:5] offset:0
	global_store_short_d16_hi v218, v114, s[4:5] offset:1024
	global_store_short v218, v115, s[4:5] offset:2048
	global_store_short_d16_hi v218, v115, s[4:5] offset:3072
	v_add_u32_e32 v218, 0x4000, v150
	global_store_short v218, v116, s[4:5] offset:0
	global_store_short_d16_hi v218, v116, s[4:5] offset:1024
	global_store_short v218, v117, s[4:5] offset:2048
	global_store_short_d16_hi v218, v117, s[4:5] offset:3072
	v_add_u32_e32 v218, 0x6000, v150
	global_store_short v218, v118, s[4:5] offset:0
	global_store_short_d16_hi v218, v118, s[4:5] offset:1024
	global_store_short v218, v119, s[4:5] offset:2048
	global_store_short_d16_hi v218, v119, s[4:5] offset:3072
	v_add_f32_e32 v96, v96, v151
	v_add_f32_e32 v97, v97, v151
	v_add_f32_e32 v98, v98, v151
	v_add_f32_e32 v99, v99, v151
	v_add_f32_e32 v100, v100, v151
	v_add_f32_e32 v101, v101, v151
	v_add_f32_e32 v102, v102, v151
	v_add_f32_e32 v103, v103, v151
	v_add_f32_e32 v104, v104, v151
	v_add_f32_e32 v105, v105, v151
	v_add_f32_e32 v106, v106, v151
	v_add_f32_e32 v107, v107, v151
	v_add_f32_e32 v108, v108, v151
	v_add_f32_e32 v109, v109, v151
	v_add_f32_e32 v110, v110, v151
	v_add_f32_e32 v111, v111, v151
	v_mul_f32_e32 v96, 0xbfb8aa3b, v96
	v_mul_f32_e32 v97, 0xbfb8aa3b, v97
	v_mul_f32_e32 v98, 0xbfb8aa3b, v98
	v_mul_f32_e32 v99, 0xbfb8aa3b, v99
	v_mul_f32_e32 v100, 0xbfb8aa3b, v100
	v_mul_f32_e32 v101, 0xbfb8aa3b, v101
	v_mul_f32_e32 v102, 0xbfb8aa3b, v102
	v_mul_f32_e32 v103, 0xbfb8aa3b, v103
	v_mul_f32_e32 v104, 0xbfb8aa3b, v104
	v_mul_f32_e32 v105, 0xbfb8aa3b, v105
	v_mul_f32_e32 v106, 0xbfb8aa3b, v106
	v_mul_f32_e32 v107, 0xbfb8aa3b, v107
	v_mul_f32_e32 v108, 0xbfb8aa3b, v108
	v_mul_f32_e32 v109, 0xbfb8aa3b, v109
	v_mul_f32_e32 v110, 0xbfb8aa3b, v110
	v_mul_f32_e32 v111, 0xbfb8aa3b, v111
	v_exp_f32_e32 v96, v96
	v_exp_f32_e32 v97, v97
	v_exp_f32_e32 v98, v98
	v_exp_f32_e32 v99, v99
	v_exp_f32_e32 v100, v100
	v_exp_f32_e32 v101, v101
	v_exp_f32_e32 v102, v102
	v_exp_f32_e32 v103, v103
	v_exp_f32_e32 v104, v104
	v_exp_f32_e32 v105, v105
	v_exp_f32_e32 v106, v106
	v_exp_f32_e32 v107, v107
	v_exp_f32_e32 v108, v108
	v_exp_f32_e32 v109, v109
	v_exp_f32_e32 v110, v110
	v_exp_f32_e32 v111, v111
	v_add_f32_e32 v96, 1.0, v96
	v_add_f32_e32 v97, 1.0, v97
	v_add_f32_e32 v98, 1.0, v98
	v_add_f32_e32 v99, 1.0, v99
	v_add_f32_e32 v100, 1.0, v100
	v_add_f32_e32 v101, 1.0, v101
	v_add_f32_e32 v102, 1.0, v102
	v_add_f32_e32 v103, 1.0, v103
	v_add_f32_e32 v104, 1.0, v104
	v_add_f32_e32 v105, 1.0, v105
	v_add_f32_e32 v106, 1.0, v106
	v_add_f32_e32 v107, 1.0, v107
	v_add_f32_e32 v108, 1.0, v108
	v_add_f32_e32 v109, 1.0, v109
	v_add_f32_e32 v110, 1.0, v110
	v_add_f32_e32 v111, 1.0, v111
	v_rcp_f32_e32 v96, v96
	v_rcp_f32_e32 v97, v97
	v_rcp_f32_e32 v98, v98
	v_rcp_f32_e32 v99, v99
	v_rcp_f32_e32 v100, v100
	v_rcp_f32_e32 v101, v101
	v_rcp_f32_e32 v102, v102
	v_rcp_f32_e32 v103, v103
	v_rcp_f32_e32 v104, v104
	v_rcp_f32_e32 v105, v105
	v_rcp_f32_e32 v106, v106
	v_rcp_f32_e32 v107, v107
	v_rcp_f32_e32 v108, v108
	v_rcp_f32_e32 v109, v109
	v_rcp_f32_e32 v110, v110
	v_rcp_f32_e32 v111, v111
	v_mul_f32_e32 v96, v201, v96
	v_mul_f32_e32 v97, v201, v97
	v_mul_f32_e32 v98, v201, v98
	v_mul_f32_e32 v99, v201, v99
	v_mul_f32_e32 v100, v201, v100
	v_mul_f32_e32 v101, v201, v101
	v_mul_f32_e32 v102, v201, v102
	v_mul_f32_e32 v103, v201, v103
	v_mul_f32_e32 v104, v201, v104
	v_mul_f32_e32 v105, v201, v105
	v_mul_f32_e32 v106, v201, v106
	v_mul_f32_e32 v107, v201, v107
	v_mul_f32_e32 v108, v201, v108
	v_mul_f32_e32 v109, v201, v109
	v_mul_f32_e32 v110, v201, v110
	v_mul_f32_e32 v111, v201, v111
	v_cvt_pk_bf16_f32 v96, v96, v97
	v_cvt_pk_bf16_f32 v97, v98, v99
	v_cvt_pk_bf16_f32 v98, v100, v101
	v_cvt_pk_bf16_f32 v99, v102, v103
	v_cvt_pk_bf16_f32 v100, v104, v105
	v_cvt_pk_bf16_f32 v101, v106, v107
	v_cvt_pk_bf16_f32 v102, v108, v109
	v_cvt_pk_bf16_f32 v103, v110, v111
	global_store_short v150, v96, s[4:5] offset:64
	global_store_short_d16_hi v150, v96, s[4:5] offset:1088
	global_store_short v150, v97, s[4:5] offset:2112
	global_store_short_d16_hi v150, v97, s[4:5] offset:3136
	v_add_u32_e32 v218, 0x2000, v150
	global_store_short v218, v98, s[4:5] offset:64
	global_store_short_d16_hi v218, v98, s[4:5] offset:1088
	global_store_short v218, v99, s[4:5] offset:2112
	global_store_short_d16_hi v218, v99, s[4:5] offset:3136
	v_add_u32_e32 v218, 0x4000, v150
	global_store_short v218, v100, s[4:5] offset:64
	global_store_short_d16_hi v218, v100, s[4:5] offset:1088
	global_store_short v218, v101, s[4:5] offset:2112
	global_store_short_d16_hi v218, v101, s[4:5] offset:3136
	v_add_u32_e32 v218, 0x6000, v150
	global_store_short v218, v102, s[4:5] offset:64
	global_store_short_d16_hi v218, v102, s[4:5] offset:1088
	global_store_short v218, v103, s[4:5] offset:2112
	global_store_short_d16_hi v218, v103, s[4:5] offset:3136
	v_add_f32_e32 v80, v80, v202
	v_add_f32_e32 v81, v81, v202
	v_add_f32_e32 v82, v82, v202
	v_add_f32_e32 v83, v83, v202
	v_add_f32_e32 v84, v84, v202
	v_add_f32_e32 v85, v85, v202
	v_add_f32_e32 v86, v86, v202
	v_add_f32_e32 v87, v87, v202
	v_add_f32_e32 v88, v88, v202
	v_add_f32_e32 v89, v89, v202
	v_add_f32_e32 v90, v90, v202
	v_add_f32_e32 v91, v91, v202
	v_add_f32_e32 v92, v92, v202
	v_add_f32_e32 v93, v93, v202
	v_add_f32_e32 v94, v94, v202
	v_add_f32_e32 v95, v95, v202
	v_mul_f32_e32 v80, 0xbfb8aa3b, v80
	v_mul_f32_e32 v81, 0xbfb8aa3b, v81
	v_mul_f32_e32 v82, 0xbfb8aa3b, v82
	v_mul_f32_e32 v83, 0xbfb8aa3b, v83
	v_mul_f32_e32 v84, 0xbfb8aa3b, v84
	v_mul_f32_e32 v85, 0xbfb8aa3b, v85
	v_mul_f32_e32 v86, 0xbfb8aa3b, v86
	v_mul_f32_e32 v87, 0xbfb8aa3b, v87
	v_mul_f32_e32 v88, 0xbfb8aa3b, v88
	v_mul_f32_e32 v89, 0xbfb8aa3b, v89
	v_mul_f32_e32 v90, 0xbfb8aa3b, v90
	v_mul_f32_e32 v91, 0xbfb8aa3b, v91
	v_mul_f32_e32 v92, 0xbfb8aa3b, v92
	v_mul_f32_e32 v93, 0xbfb8aa3b, v93
	v_mul_f32_e32 v94, 0xbfb8aa3b, v94
	v_mul_f32_e32 v95, 0xbfb8aa3b, v95
	v_exp_f32_e32 v80, v80
	v_exp_f32_e32 v81, v81
	v_exp_f32_e32 v82, v82
	v_exp_f32_e32 v83, v83
	v_exp_f32_e32 v84, v84
	v_exp_f32_e32 v85, v85
	v_exp_f32_e32 v86, v86
	v_exp_f32_e32 v87, v87
	v_exp_f32_e32 v88, v88
	v_exp_f32_e32 v89, v89
	v_exp_f32_e32 v90, v90
	v_exp_f32_e32 v91, v91
	v_exp_f32_e32 v92, v92
	v_exp_f32_e32 v93, v93
	v_exp_f32_e32 v94, v94
	v_exp_f32_e32 v95, v95
	v_add_f32_e32 v80, 1.0, v80
	v_add_f32_e32 v81, 1.0, v81
	v_add_f32_e32 v82, 1.0, v82
	v_add_f32_e32 v83, 1.0, v83
	v_add_f32_e32 v84, 1.0, v84
	v_add_f32_e32 v85, 1.0, v85
	v_add_f32_e32 v86, 1.0, v86
	v_add_f32_e32 v87, 1.0, v87
	v_add_f32_e32 v88, 1.0, v88
	v_add_f32_e32 v89, 1.0, v89
	v_add_f32_e32 v90, 1.0, v90
	v_add_f32_e32 v91, 1.0, v91
	v_add_f32_e32 v92, 1.0, v92
	v_add_f32_e32 v93, 1.0, v93
	v_add_f32_e32 v94, 1.0, v94
	v_add_f32_e32 v95, 1.0, v95
	v_rcp_f32_e32 v80, v80
	v_rcp_f32_e32 v81, v81
	v_rcp_f32_e32 v82, v82
	v_rcp_f32_e32 v83, v83
	v_rcp_f32_e32 v84, v84
	v_rcp_f32_e32 v85, v85
	v_rcp_f32_e32 v86, v86
	v_rcp_f32_e32 v87, v87
	v_rcp_f32_e32 v88, v88
	v_rcp_f32_e32 v89, v89
	v_rcp_f32_e32 v90, v90
	v_rcp_f32_e32 v91, v91
	v_rcp_f32_e32 v92, v92
	v_rcp_f32_e32 v93, v93
	v_rcp_f32_e32 v94, v94
	v_rcp_f32_e32 v95, v95
	v_mul_f32_e32 v80, v201, v80
	v_mul_f32_e32 v81, v201, v81
	v_mul_f32_e32 v82, v201, v82
	v_mul_f32_e32 v83, v201, v83
	v_mul_f32_e32 v84, v201, v84
	v_mul_f32_e32 v85, v201, v85
	v_mul_f32_e32 v86, v201, v86
	v_mul_f32_e32 v87, v201, v87
	v_mul_f32_e32 v88, v201, v88
	v_mul_f32_e32 v89, v201, v89
	v_mul_f32_e32 v90, v201, v90
	v_mul_f32_e32 v91, v201, v91
	v_mul_f32_e32 v92, v201, v92
	v_mul_f32_e32 v93, v201, v93
	v_mul_f32_e32 v94, v201, v94
	v_mul_f32_e32 v95, v201, v95
	v_cvt_pk_bf16_f32 v80, v80, v81
	v_cvt_pk_bf16_f32 v81, v82, v83
	v_cvt_pk_bf16_f32 v82, v84, v85
	v_cvt_pk_bf16_f32 v83, v86, v87
	v_cvt_pk_bf16_f32 v84, v88, v89
	v_cvt_pk_bf16_f32 v85, v90, v91
	v_cvt_pk_bf16_f32 v86, v92, v93
	v_cvt_pk_bf16_f32 v87, v94, v95
	v_add_u32_e32 v218, 0x8000, v150
	global_store_short v218, v80, s[4:5] offset:0
	global_store_short_d16_hi v218, v80, s[4:5] offset:1024
	global_store_short v218, v81, s[4:5] offset:2048
	global_store_short_d16_hi v218, v81, s[4:5] offset:3072
	v_add_u32_e32 v218, 0xa000, v150
	global_store_short v218, v82, s[4:5] offset:0
	global_store_short_d16_hi v218, v82, s[4:5] offset:1024
	global_store_short v218, v83, s[4:5] offset:2048
	global_store_short_d16_hi v218, v83, s[4:5] offset:3072
	v_add_u32_e32 v218, 0xc000, v150
	global_store_short v218, v84, s[4:5] offset:0
	global_store_short_d16_hi v218, v84, s[4:5] offset:1024
	global_store_short v218, v85, s[4:5] offset:2048
	global_store_short_d16_hi v218, v85, s[4:5] offset:3072
	v_add_u32_e32 v218, 0xe000, v150
	global_store_short v218, v86, s[4:5] offset:0
	global_store_short_d16_hi v218, v86, s[4:5] offset:1024
	global_store_short v218, v87, s[4:5] offset:2048
	global_store_short_d16_hi v218, v87, s[4:5] offset:3072
	v_add_f32_e32 v64, v64, v151
	v_add_f32_e32 v65, v65, v151
	v_add_f32_e32 v66, v66, v151
	v_add_f32_e32 v67, v67, v151
	v_add_f32_e32 v68, v68, v151
	v_add_f32_e32 v69, v69, v151
	v_add_f32_e32 v70, v70, v151
	v_add_f32_e32 v71, v71, v151
	v_add_f32_e32 v72, v72, v151
	v_add_f32_e32 v73, v73, v151
	v_add_f32_e32 v74, v74, v151
	v_add_f32_e32 v75, v75, v151
	v_add_f32_e32 v76, v76, v151
	v_add_f32_e32 v77, v77, v151
	v_add_f32_e32 v78, v78, v151
	v_add_f32_e32 v79, v79, v151
	v_mul_f32_e32 v64, 0xbfb8aa3b, v64
	v_mul_f32_e32 v65, 0xbfb8aa3b, v65
	v_mul_f32_e32 v66, 0xbfb8aa3b, v66
	v_mul_f32_e32 v67, 0xbfb8aa3b, v67
	v_mul_f32_e32 v68, 0xbfb8aa3b, v68
	v_mul_f32_e32 v69, 0xbfb8aa3b, v69
	v_mul_f32_e32 v70, 0xbfb8aa3b, v70
	v_mul_f32_e32 v71, 0xbfb8aa3b, v71
	v_mul_f32_e32 v72, 0xbfb8aa3b, v72
	v_mul_f32_e32 v73, 0xbfb8aa3b, v73
	v_mul_f32_e32 v74, 0xbfb8aa3b, v74
	v_mul_f32_e32 v75, 0xbfb8aa3b, v75
	v_mul_f32_e32 v76, 0xbfb8aa3b, v76
	v_mul_f32_e32 v77, 0xbfb8aa3b, v77
	v_mul_f32_e32 v78, 0xbfb8aa3b, v78
	v_mul_f32_e32 v79, 0xbfb8aa3b, v79
	v_exp_f32_e32 v64, v64
	v_exp_f32_e32 v65, v65
	v_exp_f32_e32 v66, v66
	v_exp_f32_e32 v67, v67
	v_exp_f32_e32 v68, v68
	v_exp_f32_e32 v69, v69
	v_exp_f32_e32 v70, v70
	v_exp_f32_e32 v71, v71
	v_exp_f32_e32 v72, v72
	v_exp_f32_e32 v73, v73
	v_exp_f32_e32 v74, v74
	v_exp_f32_e32 v75, v75
	v_exp_f32_e32 v76, v76
	v_exp_f32_e32 v77, v77
	v_exp_f32_e32 v78, v78
	v_exp_f32_e32 v79, v79
	v_add_f32_e32 v64, 1.0, v64
	v_add_f32_e32 v65, 1.0, v65
	v_add_f32_e32 v66, 1.0, v66
	v_add_f32_e32 v67, 1.0, v67
	v_add_f32_e32 v68, 1.0, v68
	v_add_f32_e32 v69, 1.0, v69
	v_add_f32_e32 v70, 1.0, v70
	v_add_f32_e32 v71, 1.0, v71
	v_add_f32_e32 v72, 1.0, v72
	v_add_f32_e32 v73, 1.0, v73
	v_add_f32_e32 v74, 1.0, v74
	v_add_f32_e32 v75, 1.0, v75
	v_add_f32_e32 v76, 1.0, v76
	v_add_f32_e32 v77, 1.0, v77
	v_add_f32_e32 v78, 1.0, v78
	v_add_f32_e32 v79, 1.0, v79
	v_rcp_f32_e32 v64, v64
	v_rcp_f32_e32 v65, v65
	v_rcp_f32_e32 v66, v66
	v_rcp_f32_e32 v67, v67
	v_rcp_f32_e32 v68, v68
	v_rcp_f32_e32 v69, v69
	v_rcp_f32_e32 v70, v70
	v_rcp_f32_e32 v71, v71
	v_rcp_f32_e32 v72, v72
	v_rcp_f32_e32 v73, v73
	v_rcp_f32_e32 v74, v74
	v_rcp_f32_e32 v75, v75
	v_rcp_f32_e32 v76, v76
	v_rcp_f32_e32 v77, v77
	v_rcp_f32_e32 v78, v78
	v_rcp_f32_e32 v79, v79
	v_mul_f32_e32 v64, v201, v64
	v_mul_f32_e32 v65, v201, v65
	v_mul_f32_e32 v66, v201, v66
	v_mul_f32_e32 v67, v201, v67
	v_mul_f32_e32 v68, v201, v68
	v_mul_f32_e32 v69, v201, v69
	v_mul_f32_e32 v70, v201, v70
	v_mul_f32_e32 v71, v201, v71
	v_mul_f32_e32 v72, v201, v72
	v_mul_f32_e32 v73, v201, v73
	v_mul_f32_e32 v74, v201, v74
	v_mul_f32_e32 v75, v201, v75
	v_mul_f32_e32 v76, v201, v76
	v_mul_f32_e32 v77, v201, v77
	v_mul_f32_e32 v78, v201, v78
	v_mul_f32_e32 v79, v201, v79
	v_cvt_pk_bf16_f32 v64, v64, v65
	v_cvt_pk_bf16_f32 v65, v66, v67
	v_cvt_pk_bf16_f32 v66, v68, v69
	v_cvt_pk_bf16_f32 v67, v70, v71
	v_cvt_pk_bf16_f32 v68, v72, v73
	v_cvt_pk_bf16_f32 v69, v74, v75
	v_cvt_pk_bf16_f32 v70, v76, v77
	v_cvt_pk_bf16_f32 v71, v78, v79
	v_add_u32_e32 v218, 0x8000, v150
	global_store_short v218, v64, s[4:5] offset:64
; template <class Epi>
; DI void gemm_tile(const GemmDesc g, int m0, int n0, unsigned char* lds, Epi& epi) {
;     ...
;     for (int j = 0; j < 2; ++j) epi(m0 + wm * 128 + i * 32 + 4 * (lane >> 5), n0 + wn * 64 + j * 32 + (lane & 31), acc[i][j]);
	global_store_short_d16_hi v218, v64, s[4:5] offset:1088
	global_store_short v218, v65, s[4:5] offset:2112
	global_store_short_d16_hi v218, v65, s[4:5] offset:3136
	v_add_u32_e32 v218, 0xa000, v150
	global_store_short v218, v66, s[4:5] offset:64
	global_store_short_d16_hi v218, v66, s[4:5] offset:1088
	global_store_short v218, v67, s[4:5] offset:2112
	global_store_short_d16_hi v218, v67, s[4:5] offset:3136
	v_add_u32_e32 v218, 0xc000, v150
	global_store_short v218, v68, s[4:5] offset:64
	global_store_short_d16_hi v218, v68, s[4:5] offset:1088
	global_store_short v218, v69, s[4:5] offset:2112
	global_store_short_d16_hi v218, v69, s[4:5] offset:3136
	v_add_u32_e32 v218, 0xe000, v150
	global_store_short v218, v70, s[4:5] offset:64
	global_store_short_d16_hi v218, v70, s[4:5] offset:1088
	global_store_short v218, v71, s[4:5] offset:2112
	global_store_short_d16_hi v218, v71, s[4:5] offset:3136
	v_add_f32_e32 v48, v48, v202
	v_add_f32_e32 v49, v49, v202
	v_add_f32_e32 v50, v50, v202
	v_add_f32_e32 v51, v51, v202
	v_add_f32_e32 v52, v52, v202
	v_add_f32_e32 v53, v53, v202
	v_add_f32_e32 v54, v54, v202
	v_add_f32_e32 v55, v55, v202
	v_add_f32_e32 v56, v56, v202
	v_add_f32_e32 v57, v57, v202
	v_add_f32_e32 v58, v58, v202
	v_add_f32_e32 v59, v59, v202
	v_add_f32_e32 v60, v60, v202
	v_add_f32_e32 v61, v61, v202
	v_add_f32_e32 v62, v62, v202
	v_add_f32_e32 v63, v63, v202
	v_mul_f32_e32 v48, 0xbfb8aa3b, v48
	v_mul_f32_e32 v49, 0xbfb8aa3b, v49
	v_mul_f32_e32 v50, 0xbfb8aa3b, v50
	v_mul_f32_e32 v51, 0xbfb8aa3b, v51
	v_mul_f32_e32 v52, 0xbfb8aa3b, v52
	v_mul_f32_e32 v53, 0xbfb8aa3b, v53
	v_mul_f32_e32 v54, 0xbfb8aa3b, v54
	v_mul_f32_e32 v55, 0xbfb8aa3b, v55
	v_mul_f32_e32 v56, 0xbfb8aa3b, v56
	v_mul_f32_e32 v57, 0xbfb8aa3b, v57
	v_mul_f32_e32 v58, 0xbfb8aa3b, v58
	v_mul_f32_e32 v59, 0xbfb8aa3b, v59
	v_mul_f32_e32 v60, 0xbfb8aa3b, v60
	v_mul_f32_e32 v61, 0xbfb8aa3b, v61
	v_mul_f32_e32 v62, 0xbfb8aa3b, v62
	v_mul_f32_e32 v63, 0xbfb8aa3b, v63
	v_exp_f32_e32 v48, v48
	v_exp_f32_e32 v49, v49
	v_exp_f32_e32 v50, v50
	v_exp_f32_e32 v51, v51
	v_exp_f32_e32 v52, v52
	v_exp_f32_e32 v53, v53
	v_exp_f32_e32 v54, v54
	v_exp_f32_e32 v55, v55
	v_exp_f32_e32 v56, v56
	v_exp_f32_e32 v57, v57
	v_exp_f32_e32 v58, v58
	v_exp_f32_e32 v59, v59
	v_exp_f32_e32 v60, v60
	v_exp_f32_e32 v61, v61
	v_exp_f32_e32 v62, v62
	v_exp_f32_e32 v63, v63
	v_add_f32_e32 v48, 1.0, v48
	v_add_f32_e32 v49, 1.0, v49
	v_add_f32_e32 v50, 1.0, v50
	v_add_f32_e32 v51, 1.0, v51
	v_add_f32_e32 v52, 1.0, v52
	v_add_f32_e32 v53, 1.0, v53
	v_add_f32_e32 v54, 1.0, v54
	v_add_f32_e32 v55, 1.0, v55
	v_add_f32_e32 v56, 1.0, v56
	v_add_f32_e32 v57, 1.0, v57
	v_add_f32_e32 v58, 1.0, v58
	v_add_f32_e32 v59, 1.0, v59
	v_add_f32_e32 v60, 1.0, v60
	v_add_f32_e32 v61, 1.0, v61
	v_add_f32_e32 v62, 1.0, v62
	v_add_f32_e32 v63, 1.0, v63
	v_rcp_f32_e32 v48, v48
	v_rcp_f32_e32 v49, v49
	v_rcp_f32_e32 v50, v50
	v_rcp_f32_e32 v51, v51
	v_rcp_f32_e32 v52, v52
	v_rcp_f32_e32 v53, v53
	v_rcp_f32_e32 v54, v54
	v_rcp_f32_e32 v55, v55
	v_rcp_f32_e32 v56, v56
	v_rcp_f32_e32 v57, v57
	v_rcp_f32_e32 v58, v58
	v_rcp_f32_e32 v59, v59
	v_rcp_f32_e32 v60, v60
	v_rcp_f32_e32 v61, v61
	v_rcp_f32_e32 v62, v62
	v_rcp_f32_e32 v63, v63
	v_mul_f32_e32 v48, v201, v48
	v_mul_f32_e32 v49, v201, v49
	v_mul_f32_e32 v50, v201, v50
	v_mul_f32_e32 v51, v201, v51
	v_mul_f32_e32 v52, v201, v52
	v_mul_f32_e32 v53, v201, v53
	v_mul_f32_e32 v54, v201, v54
	v_mul_f32_e32 v55, v201, v55
	v_mul_f32_e32 v56, v201, v56
	v_mul_f32_e32 v57, v201, v57
	v_mul_f32_e32 v58, v201, v58
	v_mul_f32_e32 v59, v201, v59
	v_mul_f32_e32 v60, v201, v60
	v_mul_f32_e32 v61, v201, v61
	v_mul_f32_e32 v62, v201, v62
	v_mul_f32_e32 v63, v201, v63
	v_cvt_pk_bf16_f32 v48, v48, v49
	v_cvt_pk_bf16_f32 v49, v50, v51
	v_cvt_pk_bf16_f32 v50, v52, v53
	v_cvt_pk_bf16_f32 v51, v54, v55
	v_cvt_pk_bf16_f32 v52, v56, v57
	v_cvt_pk_bf16_f32 v53, v58, v59
	v_cvt_pk_bf16_f32 v54, v60, v61
	v_cvt_pk_bf16_f32 v55, v62, v63
	v_add_u32_e32 v218, 0x10000, v150
	global_store_short v218, v48, s[4:5] offset:0
	global_store_short_d16_hi v218, v48, s[4:5] offset:1024
	global_store_short v218, v49, s[4:5] offset:2048
	global_store_short_d16_hi v218, v49, s[4:5] offset:3072
	v_add_u32_e32 v218, 0x12000, v150
	global_store_short v218, v50, s[4:5] offset:0
	global_store_short_d16_hi v218, v50, s[4:5] offset:1024
	global_store_short v218, v51, s[4:5] offset:2048
	global_store_short_d16_hi v218, v51, s[4:5] offset:3072
	v_add_u32_e32 v218, 0x14000, v150
	global_store_short v218, v52, s[4:5] offset:0
	global_store_short_d16_hi v218, v52, s[4:5] offset:1024
	global_store_short v218, v53, s[4:5] offset:2048
	global_store_short_d16_hi v218, v53, s[4:5] offset:3072
	v_add_u32_e32 v218, 0x16000, v150
	global_store_short v218, v54, s[4:5] offset:0
	global_store_short_d16_hi v218, v54, s[4:5] offset:1024
	global_store_short v218, v55, s[4:5] offset:2048
	global_store_short_d16_hi v218, v55, s[4:5] offset:3072
	v_add_f32_e32 v16, v16, v202
	v_add_f32_e32 v17, v17, v202
	v_add_f32_e32 v18, v18, v202
	v_add_f32_e32 v19, v19, v202
	v_add_f32_e32 v20, v20, v202
	v_add_f32_e32 v21, v21, v202
	v_add_f32_e32 v22, v22, v202
	v_add_f32_e32 v23, v23, v202
	v_add_f32_e32 v24, v24, v202
	v_add_f32_e32 v25, v25, v202
	v_add_f32_e32 v26, v26, v202
	v_add_f32_e32 v27, v27, v202
	v_add_f32_e32 v28, v28, v202
	v_add_f32_e32 v29, v29, v202
	v_add_f32_e32 v30, v30, v202
	v_add_f32_e32 v31, v31, v202
	v_mul_f32_e32 v16, 0xbfb8aa3b, v16
	v_mul_f32_e32 v17, 0xbfb8aa3b, v17
	v_mul_f32_e32 v18, 0xbfb8aa3b, v18
	v_mul_f32_e32 v19, 0xbfb8aa3b, v19
	v_mul_f32_e32 v20, 0xbfb8aa3b, v20
	v_mul_f32_e32 v21, 0xbfb8aa3b, v21
	v_mul_f32_e32 v22, 0xbfb8aa3b, v22
	v_mul_f32_e32 v23, 0xbfb8aa3b, v23
	v_mul_f32_e32 v24, 0xbfb8aa3b, v24
	v_mul_f32_e32 v25, 0xbfb8aa3b, v25
	v_mul_f32_e32 v26, 0xbfb8aa3b, v26
	v_mul_f32_e32 v27, 0xbfb8aa3b, v27
	v_mul_f32_e32 v28, 0xbfb8aa3b, v28
	v_mul_f32_e32 v29, 0xbfb8aa3b, v29
	v_mul_f32_e32 v30, 0xbfb8aa3b, v30
	v_mul_f32_e32 v31, 0xbfb8aa3b, v31
	v_exp_f32_e32 v16, v16
	v_exp_f32_e32 v17, v17
	v_exp_f32_e32 v18, v18
	v_exp_f32_e32 v19, v19
	v_exp_f32_e32 v20, v20
	v_exp_f32_e32 v21, v21
	v_exp_f32_e32 v22, v22
	v_exp_f32_e32 v23, v23
	v_exp_f32_e32 v24, v24
	v_exp_f32_e32 v25, v25
	v_exp_f32_e32 v26, v26
	v_exp_f32_e32 v27, v27
	v_exp_f32_e32 v28, v28
	v_exp_f32_e32 v29, v29
	v_exp_f32_e32 v30, v30
	v_exp_f32_e32 v31, v31
	v_add_f32_e32 v16, 1.0, v16
	v_add_f32_e32 v17, 1.0, v17
	v_add_f32_e32 v18, 1.0, v18
	v_add_f32_e32 v19, 1.0, v19
	v_add_f32_e32 v20, 1.0, v20
	v_add_f32_e32 v21, 1.0, v21
	v_add_f32_e32 v22, 1.0, v22
	v_add_f32_e32 v23, 1.0, v23
	v_add_f32_e32 v24, 1.0, v24
	v_add_f32_e32 v25, 1.0, v25
	v_add_f32_e32 v26, 1.0, v26
	v_add_f32_e32 v27, 1.0, v27
	v_add_f32_e32 v28, 1.0, v28
	v_add_f32_e32 v29, 1.0, v29
	v_add_f32_e32 v30, 1.0, v30
	v_add_f32_e32 v31, 1.0, v31
	v_rcp_f32_e32 v16, v16
	v_rcp_f32_e32 v17, v17
	v_rcp_f32_e32 v18, v18
	v_rcp_f32_e32 v19, v19
	v_rcp_f32_e32 v20, v20
	v_rcp_f32_e32 v21, v21
	v_rcp_f32_e32 v22, v22
	v_rcp_f32_e32 v23, v23
	v_rcp_f32_e32 v24, v24
	v_rcp_f32_e32 v25, v25
	v_rcp_f32_e32 v26, v26
	v_rcp_f32_e32 v27, v27
	v_rcp_f32_e32 v28, v28
	v_rcp_f32_e32 v29, v29
	v_rcp_f32_e32 v30, v30
	v_rcp_f32_e32 v31, v31
	v_mul_f32_e32 v16, v201, v16
	v_mul_f32_e32 v17, v201, v17
	v_mul_f32_e32 v18, v201, v18
	v_mul_f32_e32 v19, v201, v19
	v_mul_f32_e32 v20, v201, v20
	v_mul_f32_e32 v21, v201, v21
	v_mul_f32_e32 v22, v201, v22
	v_mul_f32_e32 v23, v201, v23
	v_mul_f32_e32 v24, v201, v24
	v_mul_f32_e32 v25, v201, v25
	v_mul_f32_e32 v26, v201, v26
	v_mul_f32_e32 v27, v201, v27
	v_mul_f32_e32 v28, v201, v28
	v_mul_f32_e32 v29, v201, v29
	v_mul_f32_e32 v30, v201, v30
	v_mul_f32_e32 v31, v201, v31
	v_cvt_pk_bf16_f32 v16, v16, v17
	v_cvt_pk_bf16_f32 v17, v18, v19
	v_cvt_pk_bf16_f32 v18, v20, v21
	v_cvt_pk_bf16_f32 v19, v22, v23
	v_cvt_pk_bf16_f32 v20, v24, v25
	v_cvt_pk_bf16_f32 v21, v26, v27
	v_cvt_pk_bf16_f32 v22, v28, v29
	v_cvt_pk_bf16_f32 v23, v30, v31
	v_add_u32_e32 v218, 0x18000, v150
	global_store_short v218, v16, s[4:5] offset:0
	global_store_short_d16_hi v218, v16, s[4:5] offset:1024
	global_store_short v218, v17, s[4:5] offset:2048
	global_store_short_d16_hi v218, v17, s[4:5] offset:3072
	v_add_u32_e32 v218, 0x1a000, v150
	global_store_short v218, v18, s[4:5] offset:0
	global_store_short_d16_hi v218, v18, s[4:5] offset:1024
	global_store_short v218, v19, s[4:5] offset:2048
	global_store_short_d16_hi v218, v19, s[4:5] offset:3072
	v_add_u32_e32 v218, 0x1c000, v150
	global_store_short v218, v20, s[4:5] offset:0
	global_store_short_d16_hi v218, v20, s[4:5] offset:1024
	global_store_short v218, v21, s[4:5] offset:2048
	global_store_short_d16_hi v218, v21, s[4:5] offset:3072
	v_add_u32_e32 v218, 0x1e000, v150
	global_store_short v218, v22, s[4:5] offset:0
	global_store_short_d16_hi v218, v22, s[4:5] offset:1024
	global_store_short v218, v23, s[4:5] offset:2048
	global_store_short_d16_hi v218, v23, s[4:5] offset:3072
	v_add_f32_e32 v32, v32, v151
	v_add_f32_e32 v33, v33, v151
	v_add_f32_e32 v34, v34, v151
	v_add_f32_e32 v35, v35, v151
	v_add_f32_e32 v36, v36, v151
	v_add_f32_e32 v37, v37, v151
	v_add_f32_e32 v38, v38, v151
	v_add_f32_e32 v39, v39, v151
	v_add_f32_e32 v40, v40, v151
	v_add_f32_e32 v41, v41, v151
	v_add_f32_e32 v42, v42, v151
	v_add_f32_e32 v43, v43, v151
	v_add_f32_e32 v44, v44, v151
	v_add_f32_e32 v45, v45, v151
	v_add_f32_e32 v46, v46, v151
	v_add_f32_e32 v47, v47, v151
	v_mul_f32_e32 v32, 0xbfb8aa3b, v32
	v_mul_f32_e32 v33, 0xbfb8aa3b, v33
	v_mul_f32_e32 v34, 0xbfb8aa3b, v34
	v_mul_f32_e32 v35, 0xbfb8aa3b, v35
	v_mul_f32_e32 v36, 0xbfb8aa3b, v36
	v_mul_f32_e32 v37, 0xbfb8aa3b, v37
	v_mul_f32_e32 v38, 0xbfb8aa3b, v38
	v_mul_f32_e32 v39, 0xbfb8aa3b, v39
	v_mul_f32_e32 v40, 0xbfb8aa3b, v40
	v_mul_f32_e32 v41, 0xbfb8aa3b, v41
	v_mul_f32_e32 v42, 0xbfb8aa3b, v42
	v_mul_f32_e32 v43, 0xbfb8aa3b, v43
	v_mul_f32_e32 v44, 0xbfb8aa3b, v44
	v_mul_f32_e32 v45, 0xbfb8aa3b, v45
	v_mul_f32_e32 v46, 0xbfb8aa3b, v46
	v_mul_f32_e32 v47, 0xbfb8aa3b, v47
	v_exp_f32_e32 v32, v32
	v_exp_f32_e32 v33, v33
	v_exp_f32_e32 v34, v34
	v_exp_f32_e32 v35, v35
	v_exp_f32_e32 v36, v36
	v_exp_f32_e32 v37, v37
	v_exp_f32_e32 v38, v38
	v_exp_f32_e32 v39, v39
	v_exp_f32_e32 v40, v40
	v_exp_f32_e32 v41, v41
	v_exp_f32_e32 v42, v42
	v_exp_f32_e32 v43, v43
	v_exp_f32_e32 v44, v44
	v_exp_f32_e32 v45, v45
	v_exp_f32_e32 v46, v46
	v_exp_f32_e32 v47, v47
	v_add_f32_e32 v32, 1.0, v32
	v_add_f32_e32 v33, 1.0, v33
	v_add_f32_e32 v34, 1.0, v34
	v_add_f32_e32 v35, 1.0, v35
	v_add_f32_e32 v36, 1.0, v36
	v_add_f32_e32 v37, 1.0, v37
	v_add_f32_e32 v38, 1.0, v38
	v_add_f32_e32 v39, 1.0, v39
	v_add_f32_e32 v40, 1.0, v40
	v_add_f32_e32 v41, 1.0, v41
	v_add_f32_e32 v42, 1.0, v42
	v_add_f32_e32 v43, 1.0, v43
	v_add_f32_e32 v44, 1.0, v44
	v_add_f32_e32 v45, 1.0, v45
	v_add_f32_e32 v46, 1.0, v46
	v_add_f32_e32 v47, 1.0, v47
	v_rcp_f32_e32 v32, v32
	v_rcp_f32_e32 v33, v33
	v_rcp_f32_e32 v34, v34
	v_rcp_f32_e32 v35, v35
	v_rcp_f32_e32 v36, v36
	v_rcp_f32_e32 v37, v37
	v_rcp_f32_e32 v38, v38
	v_rcp_f32_e32 v39, v39
	v_rcp_f32_e32 v40, v40
	v_rcp_f32_e32 v41, v41
	v_rcp_f32_e32 v42, v42
	v_rcp_f32_e32 v43, v43
	v_rcp_f32_e32 v44, v44
	v_rcp_f32_e32 v45, v45
	v_rcp_f32_e32 v46, v46
	v_rcp_f32_e32 v47, v47
	v_mul_f32_e32 v32, v201, v32
	v_mul_f32_e32 v33, v201, v33
	v_mul_f32_e32 v34, v201, v34
	v_mul_f32_e32 v35, v201, v35
	v_mul_f32_e32 v36, v201, v36
	v_mul_f32_e32 v37, v201, v37
	v_mul_f32_e32 v38, v201, v38
	v_mul_f32_e32 v39, v201, v39
	v_mul_f32_e32 v40, v201, v40
	v_mul_f32_e32 v41, v201, v41
	v_mul_f32_e32 v42, v201, v42
	v_mul_f32_e32 v43, v201, v43
	v_mul_f32_e32 v44, v201, v44
	v_mul_f32_e32 v45, v201, v45
	v_mul_f32_e32 v46, v201, v46
	v_mul_f32_e32 v47, v201, v47
	v_cvt_pk_bf16_f32 v32, v32, v33
	v_cvt_pk_bf16_f32 v33, v34, v35
	v_cvt_pk_bf16_f32 v34, v36, v37
	v_cvt_pk_bf16_f32 v35, v38, v39
	v_cvt_pk_bf16_f32 v36, v40, v41
	v_cvt_pk_bf16_f32 v37, v42, v43
	v_cvt_pk_bf16_f32 v38, v44, v45
	v_cvt_pk_bf16_f32 v39, v46, v47
	v_add_u32_e32 v218, 0x10000, v150
	global_store_short v218, v32, s[4:5] offset:64
	global_store_short_d16_hi v218, v32, s[4:5] offset:1088
	global_store_short v218, v33, s[4:5] offset:2112
	global_store_short_d16_hi v218, v33, s[4:5] offset:3136
	v_add_u32_e32 v218, 0x12000, v150
	global_store_short v218, v34, s[4:5] offset:64
	global_store_short_d16_hi v218, v34, s[4:5] offset:1088
	global_store_short v218, v35, s[4:5] offset:2112
	global_store_short_d16_hi v218, v35, s[4:5] offset:3136
	v_add_u32_e32 v218, 0x14000, v150
	global_store_short v218, v36, s[4:5] offset:64
	global_store_short_d16_hi v218, v36, s[4:5] offset:1088
	global_store_short v218, v37, s[4:5] offset:2112
	global_store_short_d16_hi v218, v37, s[4:5] offset:3136
	v_add_u32_e32 v218, 0x16000, v150
	global_store_short v218, v38, s[4:5] offset:64
	global_store_short_d16_hi v218, v38, s[4:5] offset:1088
	global_store_short v218, v39, s[4:5] offset:2112
	global_store_short_d16_hi v218, v39, s[4:5] offset:3136
	v_add_f32_e32 v0, v0, v151
	v_add_f32_e32 v1, v1, v151
	v_add_f32_e32 v2, v2, v151
	v_add_f32_e32 v3, v3, v151
	v_add_f32_e32 v4, v4, v151
	v_add_f32_e32 v5, v5, v151
	v_add_f32_e32 v6, v6, v151
	v_add_f32_e32 v7, v7, v151
	v_add_f32_e32 v8, v8, v151
	v_add_f32_e32 v9, v9, v151
	v_add_f32_e32 v10, v10, v151
	v_add_f32_e32 v11, v11, v151
	v_add_f32_e32 v12, v12, v151
	v_add_f32_e32 v13, v13, v151
	v_add_f32_e32 v14, v14, v151
	v_add_f32_e32 v15, v15, v151
	v_mul_f32_e32 v0, 0xbfb8aa3b, v0
	v_mul_f32_e32 v1, 0xbfb8aa3b, v1
	v_mul_f32_e32 v2, 0xbfb8aa3b, v2
	v_mul_f32_e32 v3, 0xbfb8aa3b, v3
	v_mul_f32_e32 v4, 0xbfb8aa3b, v4
	v_mul_f32_e32 v5, 0xbfb8aa3b, v5
	v_mul_f32_e32 v6, 0xbfb8aa3b, v6
	v_mul_f32_e32 v7, 0xbfb8aa3b, v7
	v_mul_f32_e32 v8, 0xbfb8aa3b, v8
	v_mul_f32_e32 v9, 0xbfb8aa3b, v9
	v_mul_f32_e32 v10, 0xbfb8aa3b, v10
	v_mul_f32_e32 v11, 0xbfb8aa3b, v11
	v_mul_f32_e32 v12, 0xbfb8aa3b, v12
	v_mul_f32_e32 v13, 0xbfb8aa3b, v13
	v_mul_f32_e32 v14, 0xbfb8aa3b, v14
	v_mul_f32_e32 v15, 0xbfb8aa3b, v15
	v_exp_f32_e32 v0, v0
	v_exp_f32_e32 v1, v1
	v_exp_f32_e32 v2, v2
	v_exp_f32_e32 v3, v3
	v_exp_f32_e32 v4, v4
	v_exp_f32_e32 v5, v5
	v_exp_f32_e32 v6, v6
	v_exp_f32_e32 v7, v7
	v_exp_f32_e32 v8, v8
	v_exp_f32_e32 v9, v9
	v_exp_f32_e32 v10, v10
	v_exp_f32_e32 v11, v11
	v_exp_f32_e32 v12, v12
	v_exp_f32_e32 v13, v13
	v_exp_f32_e32 v14, v14
	v_exp_f32_e32 v15, v15
	v_add_f32_e32 v0, 1.0, v0
	v_add_f32_e32 v1, 1.0, v1
	v_add_f32_e32 v2, 1.0, v2
	v_add_f32_e32 v3, 1.0, v3
	v_add_f32_e32 v4, 1.0, v4
	v_add_f32_e32 v5, 1.0, v5
	v_add_f32_e32 v6, 1.0, v6
	v_add_f32_e32 v7, 1.0, v7
	v_add_f32_e32 v8, 1.0, v8
	v_add_f32_e32 v9, 1.0, v9
	v_add_f32_e32 v10, 1.0, v10
	v_add_f32_e32 v11, 1.0, v11
	v_add_f32_e32 v12, 1.0, v12
	v_add_f32_e32 v13, 1.0, v13
	v_add_f32_e32 v14, 1.0, v14
	v_add_f32_e32 v15, 1.0, v15
	v_rcp_f32_e32 v0, v0
	v_rcp_f32_e32 v1, v1
	v_rcp_f32_e32 v2, v2
	v_rcp_f32_e32 v3, v3
	v_rcp_f32_e32 v4, v4
	v_rcp_f32_e32 v5, v5
	v_rcp_f32_e32 v6, v6
	v_rcp_f32_e32 v7, v7
	v_rcp_f32_e32 v8, v8
	v_rcp_f32_e32 v9, v9
	v_rcp_f32_e32 v10, v10
	v_rcp_f32_e32 v11, v11
	v_rcp_f32_e32 v12, v12
	v_rcp_f32_e32 v13, v13
	v_rcp_f32_e32 v14, v14
	v_rcp_f32_e32 v15, v15
	v_mul_f32_e32 v0, v201, v0
	v_mul_f32_e32 v1, v201, v1
	v_mul_f32_e32 v2, v201, v2
	v_mul_f32_e32 v3, v201, v3
	v_mul_f32_e32 v4, v201, v4
	v_mul_f32_e32 v5, v201, v5
	v_mul_f32_e32 v6, v201, v6
	v_mul_f32_e32 v7, v201, v7
	v_mul_f32_e32 v8, v201, v8
	v_mul_f32_e32 v9, v201, v9
	v_mul_f32_e32 v10, v201, v10
	v_mul_f32_e32 v11, v201, v11
	v_mul_f32_e32 v12, v201, v12
	v_mul_f32_e32 v13, v201, v13
	v_mul_f32_e32 v14, v201, v14
	v_mul_f32_e32 v15, v201, v15
	v_cvt_pk_bf16_f32 v0, v0, v1
	v_cvt_pk_bf16_f32 v1, v2, v3
	v_cvt_pk_bf16_f32 v2, v4, v5
	v_cvt_pk_bf16_f32 v3, v6, v7
	v_cvt_pk_bf16_f32 v4, v8, v9
	v_cvt_pk_bf16_f32 v5, v10, v11
	v_cvt_pk_bf16_f32 v6, v12, v13
	v_cvt_pk_bf16_f32 v7, v14, v15
	v_add_u32_e32 v218, 0x18000, v150
	global_store_short v218, v0, s[4:5] offset:64
	global_store_short_d16_hi v218, v0, s[4:5] offset:1088
	global_store_short v218, v1, s[4:5] offset:2112
	global_store_short_d16_hi v218, v1, s[4:5] offset:3136
	v_add_u32_e32 v218, 0x1a000, v150
	global_store_short v218, v2, s[4:5] offset:64
	global_store_short_d16_hi v218, v2, s[4:5] offset:1088
	global_store_short v218, v3, s[4:5] offset:2112
	global_store_short_d16_hi v218, v3, s[4:5] offset:3136
	v_add_u32_e32 v218, 0x1c000, v150
	global_store_short v218, v4, s[4:5] offset:64
	global_store_short_d16_hi v218, v4, s[4:5] offset:1088
	global_store_short v218, v5, s[4:5] offset:2112
	global_store_short_d16_hi v218, v5, s[4:5] offset:3136
	v_add_u32_e32 v218, 0x1e000, v150
	global_store_short v218, v6, s[4:5] offset:64
	global_store_short_d16_hi v218, v6, s[4:5] offset:1088
	global_store_short v218, v7, s[4:5] offset:2112
	global_store_short_d16_hi v218, v7, s[4:5] offset:3136
	s_branch .LBB0_755
